# STAGGER-P2: the 176 workgroups without a sixth GEMM1a tile start the phase 3 x s_sleep 127 later so their store bursts do not coincide with the critical workgroups' (on GATE-AHEAD)
# speedup vs baseline: 1.0045x; 1.0045x over previous
.LBB0_201:
	s_cmp_lt_i32 s62, 3
	s_cselect_b64 s[0:1], -1, 0
	s_and_b64 s[8:9], s[0:1], s[4:5]
	s_andn2_b64 vcc, exec, s[8:9]
	s_cbranch_vccnz .LBB0_266
	s_cmpk_lt_i32 s75, 0x50
	s_cbranch_scc1 .Lstagp2_go
	s_sleep 127
	s_sleep 127
	s_sleep 127
.Lstagp2_go:
	s_cmpk_lt_i32 s75, 0x550
	s_cselect_b64 s[4:5], -1, 0
	s_cmpk_gt_i32 s75, 0x54f
	v_readfirstlane_b32 s18, v0
	s_cbranch_scc1 .LBB0_204
	s_ashr_i32 s0, s75, 31
	s_lshr_b32 s0, s0, 29
	s_add_i32 s0, s75, s0
	s_ashr_i32 s1, s0, 3
	s_and_b32 s0, s0, -8
	s_sub_i32 s0, s75, s0
	s_cmp_lt_i32 s0, 0
	s_movk_i32 s2, 0xab
	s_cselect_b32 s2, s2, 0xaa
	s_mul_i32 s0, s0, s2
	s_add_i32 s0, s0, s1
	s_mul_hi_i32 s1, s0, 0x78787879
	s_lshr_b32 s2, s1, 31
	s_ashr_i32 s1, s1, 6
	s_add_i32 s1, s1, s2
	s_lshl_b32 s2, s1, 3
	s_mulk_i32 s1, 0x88
	s_sub_i32 s0, s0, s1
	s_sext_i32_i16 s1, s0
	s_bfe_u32 s1, s1, 0x3001c
	s_add_i32 s1, s0, s1
	s_sext_i32_i16 s3, s1
	s_and_b32 s1, s1, 0xfff8
	s_sub_i32 s0, s0, s1
	s_sext_i32_i16 s0, s0
	s_add_i32 s28, s2, s0
	s_ashr_i32 s6, s3, 3
